# hazard windows after the last QK MFMA filled by the early V-read blocks (s_nop 10/7 shrunk in MLA; SWA V reads moved into the window); stacked on the full stack
# speedup vs baseline: 1.0005x; 1.0005x over previous
.LBB0_1221:
	s_or_b32 s86, s51, s50
	s_cmp_gt_u32 s86, s57
	s_cbranch_scc1 .LBB0_1220
	v_or_b32_e32 v5, s51, v203
	s_movk_i32 s87, 0x190
	v_mad_u32_u24 v5, v5, s87, v3
	ds_read_b128 v[6:9], v5
	ds_read_b128 v[10:13], v5 offset:32
	ds_read_b128 v[14:17], v5 offset:64
	ds_read_b128 v[216:219], v5 offset:96
	ds_read_b128 v[220:223], v5 offset:128
	ds_read_b128 v[224:227], v5 offset:160
	ds_read_b128 v[228:231], v5 offset:192
	ds_read_b128 v[232:235], v5 offset:224
	s_waitcnt lgkmcnt(7)
	v_mfma_f32_32x32x16_bf16 v[82:97], v[6:9], v[98:101], 0
	ds_read_b128 v[6:9], v5 offset:256
	s_waitcnt lgkmcnt(7)
	v_mfma_f32_32x32x16_bf16 v[82:97], v[10:13], v[102:105], v[82:97]
	ds_read_b128 v[10:13], v5 offset:288
	s_waitcnt lgkmcnt(7)
	v_mfma_f32_32x32x16_bf16 v[82:97], v[14:17], v[106:109], v[82:97]
	ds_read_b128 v[14:17], v5 offset:320
	s_waitcnt lgkmcnt(7)
	v_mfma_f32_32x32x16_bf16 v[82:97], v[216:219], v[110:113], v[82:97]
	ds_read_b128 v[216:219], v5 offset:352
	s_waitcnt lgkmcnt(7)
	v_mfma_f32_32x32x16_bf16 v[82:97], v[220:223], v[114:117], v[82:97]
	s_or_b32 s87, s86, 31
	s_cmp_le_u32 s87, s24
	s_waitcnt lgkmcnt(6)
	v_mfma_f32_32x32x16_bf16 v[82:97], v[224:227], v[118:121], v[82:97]
	s_waitcnt lgkmcnt(5)
	v_mfma_f32_32x32x16_bf16 v[82:97], v[228:231], v[122:125], v[82:97]
	s_waitcnt lgkmcnt(4)
	v_mfma_f32_32x32x16_bf16 v[82:97], v[232:235], v[126:129], v[82:97]
	s_waitcnt lgkmcnt(3)
	v_mfma_f32_32x32x16_bf16 v[82:97], v[6:9], v[130:133], v[82:97]
	s_waitcnt lgkmcnt(2)
	v_mfma_f32_32x32x16_bf16 v[82:97], v[10:13], v[134:137], v[82:97]
	s_waitcnt lgkmcnt(1)
	v_mfma_f32_32x32x16_bf16 v[82:97], v[14:17], v[138:141], v[82:97]
	s_waitcnt lgkmcnt(0)
	v_mfma_f32_32x32x16_bf16 v[82:97], v[216:219], v[142:145], v[82:97]
	v_or_b32_e32 v235, s51, v205
	s_movk_i32 s98, 0x140
	v_mad_u32_u24 v235, v235, s98, v4
	ds_read_b64_tr_b16 v[238:239], v235 offset:25600
	ds_read_b64_tr_b16 v[240:241], v235 offset:28160
	ds_read_b64_tr_b16 v[242:243], v235 offset:30720
	ds_read_b64_tr_b16 v[244:245], v235 offset:33280
	ds_read_b64_tr_b16 v[246:247], v235 offset:25664
	ds_read_b64_tr_b16 v[248:249], v235 offset:28224
	s_cbranch_scc1 .LBB0_1224
	v_or_b32_e32 v5, s86, v208
	v_cmp_lt_u32_e32 vcc, v5, v213
	v_or_b32_e32 v6, 2, v5
	s_nop 0
	v_cndmask_b32_e32 v83, v212, v83, vcc
	v_cmp_le_u32_e32 vcc, v5, v213
	s_nop 1
	v_cndmask_b32_e32 v82, v212, v82, vcc
	v_cmp_le_u32_e32 vcc, v6, v213
	v_or_b32_e32 v6, 3, v5
	s_nop 0
	v_cndmask_b32_e32 v84, v212, v84, vcc
	v_cmp_le_u32_e32 vcc, v6, v213
	v_or_b32_e32 v6, 8, v5
	s_nop 0
	v_cndmask_b32_e32 v85, v212, v85, vcc
	v_cmp_le_u32_e32 vcc, v6, v213
	v_or_b32_e32 v6, 9, v5
	s_nop 0
	v_cndmask_b32_e32 v86, v212, v86, vcc
	v_cmp_le_u32_e32 vcc, v6, v213
	v_or_b32_e32 v6, 10, v5
	s_nop 0
	v_cndmask_b32_e32 v87, v212, v87, vcc
	v_cmp_le_u32_e32 vcc, v6, v213
	v_or_b32_e32 v6, 11, v5
	s_nop 0
	v_cndmask_b32_e32 v88, v212, v88, vcc
	v_cmp_le_u32_e32 vcc, v6, v213
	v_or_b32_e32 v6, 16, v5
	s_nop 0
	v_cndmask_b32_e32 v89, v212, v89, vcc
	v_cmp_le_u32_e32 vcc, v6, v213
	v_or_b32_e32 v6, 17, v5
	s_nop 0
	v_cndmask_b32_e32 v90, v212, v90, vcc
	v_cmp_le_u32_e32 vcc, v6, v213
	v_or_b32_e32 v6, 18, v5
	s_nop 0
	v_cndmask_b32_e32 v91, v212, v91, vcc
	v_cmp_le_u32_e32 vcc, v6, v213
	v_or_b32_e32 v6, 19, v5
	s_nop 0
	v_cndmask_b32_e32 v92, v212, v92, vcc
	v_cmp_le_u32_e32 vcc, v6, v213
	v_or_b32_e32 v6, 24, v5
	s_nop 0
	v_cndmask_b32_e32 v93, v212, v93, vcc
	v_cmp_le_u32_e32 vcc, v6, v213
	v_or_b32_e32 v6, 25, v5
	s_nop 0
	v_cndmask_b32_e32 v94, v212, v94, vcc
	v_cmp_le_u32_e32 vcc, v6, v213
	v_or_b32_e32 v6, 26, v5
	v_or_b32_e32 v5, 27, v5
	v_cndmask_b32_e32 v95, v212, v95, vcc
	v_cmp_le_u32_e32 vcc, v6, v213
	s_nop 1
	v_cndmask_b32_e32 v96, v212, v96, vcc
	v_cmp_le_u32_e32 vcc, v5, v213
	s_nop 1
	v_cndmask_b32_e32 v97, v212, v97, vcc
.LBB0_1224:
	s_nop 2
	v_max_f32_e32 v5, v83, v83
	v_max_f32_e32 v6, v82, v82
	v_max_f32_e32 v5, v6, v5
	v_max3_f32 v5, v5, v84, v85
	v_max3_f32 v5, v5, v86, v87
	v_max3_f32 v5, v5, v88, v89
	v_max3_f32 v5, v5, v90, v91
	v_max3_f32 v5, v5, v92, v93
	v_max3_f32 v5, v5, v94, v95
	v_max3_f32 v5, v5, v96, v97
	v_mov_b32_e32 v6, v5
	s_nop 1
	v_permlane32_swap_b32_e32 v5, v6
	v_max_f32_e32 v6, v6, v6
	v_max_f32_e32 v5, v5, v5
	v_max_f32_e32 v5, v5, v6
	v_add_f32_e32 v6, 0x41000000, v215
	v_cmp_gt_f32_e32 vcc, v5, v6
	s_cbranch_vccz .LBB0_1226
	v_max_f32_e32 v5, v5, v5
	v_max_f32_e32 v6, v215, v215
	v_max_f32_e32 v5, v6, v5
	v_sub_f32_e32 v6, v215, v5
	v_exp_f32_e32 v6, v6
	v_mov_b32_e32 v215, v5
	v_pk_mul_f32 v[80:81], v[80:81], v[6:7] op_sel_hi:[1,0]
	v_pk_mul_f32 v[78:79], v[78:79], v[6:7] op_sel_hi:[1,0]
	v_pk_mul_f32 v[76:77], v[76:77], v[6:7] op_sel_hi:[1,0]
	v_pk_mul_f32 v[74:75], v[74:75], v[6:7] op_sel_hi:[1,0]
	v_pk_mul_f32 v[72:73], v[72:73], v[6:7] op_sel_hi:[1,0]
	v_pk_mul_f32 v[70:71], v[70:71], v[6:7] op_sel_hi:[1,0]
	v_pk_mul_f32 v[68:69], v[68:69], v[6:7] op_sel_hi:[1,0]
	v_pk_mul_f32 v[66:67], v[66:67], v[6:7] op_sel_hi:[1,0]
	v_pk_mul_f32 v[64:65], v[64:65], v[6:7] op_sel_hi:[1,0]
	v_pk_mul_f32 v[62:63], v[62:63], v[6:7] op_sel_hi:[1,0]
	v_pk_mul_f32 v[60:61], v[60:61], v[6:7] op_sel_hi:[1,0]
	v_pk_mul_f32 v[58:59], v[58:59], v[6:7] op_sel_hi:[1,0]
	v_pk_mul_f32 v[56:57], v[56:57], v[6:7] op_sel_hi:[1,0]
	v_pk_mul_f32 v[54:55], v[54:55], v[6:7] op_sel_hi:[1,0]
	v_pk_mul_f32 v[52:53], v[52:53], v[6:7] op_sel_hi:[1,0]
	v_pk_mul_f32 v[50:51], v[50:51], v[6:7] op_sel_hi:[1,0]
	v_pk_mul_f32 v[48:49], v[48:49], v[6:7] op_sel_hi:[1,0]
	v_pk_mul_f32 v[46:47], v[46:47], v[6:7] op_sel_hi:[1,0]
	v_pk_mul_f32 v[44:45], v[44:45], v[6:7] op_sel_hi:[1,0]
	v_pk_mul_f32 v[42:43], v[42:43], v[6:7] op_sel_hi:[1,0]
	v_pk_mul_f32 v[40:41], v[40:41], v[6:7] op_sel_hi:[1,0]
	v_pk_mul_f32 v[38:39], v[38:39], v[6:7] op_sel_hi:[1,0]
	v_pk_mul_f32 v[36:37], v[36:37], v[6:7] op_sel_hi:[1,0]
	v_pk_mul_f32 v[34:35], v[34:35], v[6:7] op_sel_hi:[1,0]
	v_pk_mul_f32 v[32:33], v[32:33], v[6:7] op_sel_hi:[1,0]
	v_pk_mul_f32 v[30:31], v[30:31], v[6:7] op_sel_hi:[1,0]
	v_pk_mul_f32 v[28:29], v[28:29], v[6:7] op_sel_hi:[1,0]
	v_pk_mul_f32 v[26:27], v[26:27], v[6:7] op_sel_hi:[1,0]
	v_pk_mul_f32 v[24:25], v[24:25], v[6:7] op_sel_hi:[1,0]
	v_pk_mul_f32 v[22:23], v[22:23], v[6:7] op_sel_hi:[1,0]
	v_pk_mul_f32 v[20:21], v[20:21], v[6:7] op_sel_hi:[1,0]
	v_pk_mul_f32 v[18:19], v[18:19], v[6:7] op_sel_hi:[1,0]
	v_mul_f32_e32 v214, v214, v6

.LBB0_1289:
	v_sub_f32_e32 v53, v175, v159
	v_exp_f32_e32 v53, v53
	v_sub_f32_e32 v55, v174, v159
	v_exp_f32_e32 v55, v55
	v_sub_f32_e32 v52, v52, v159
	v_exp_f32_e32 v52, v52
	v_sub_f32_e32 v51, v51, v159
	v_exp_f32_e32 v51, v51
	v_sub_f32_e32 v50, v50, v159
	v_add_f32_e32 v54, 0, v53
	v_exp_f32_e32 v50, v50
	v_sub_f32_e32 v17, v17, v159
	v_add_f32_e32 v54, v55, v54
	v_exp_f32_e32 v17, v17
	v_sub_f32_e32 v16, v16, v159
	v_add_f32_e32 v54, v52, v54
	v_exp_f32_e32 v16, v16
	v_sub_f32_e32 v15, v15, v159
	v_add_f32_e32 v54, v51, v54
	v_exp_f32_e32 v15, v15
	v_sub_f32_e32 v14, v14, v159
	v_add_f32_e32 v54, v50, v54
	v_exp_f32_e32 v14, v14
	v_sub_f32_e32 v13, v13, v159
	v_add_f32_e32 v54, v17, v54
	v_exp_f32_e32 v13, v13
	v_sub_f32_e32 v12, v12, v159
	v_add_f32_e32 v54, v16, v54
	v_exp_f32_e32 v56, v12
	v_add_f32_e32 v54, v15, v54
	v_add_f32_e32 v54, v14, v54
	v_add_f32_e32 v54, v13, v54
	v_sub_f32_e32 v11, v11, v159
	v_add_f32_e32 v12, v56, v54
	v_exp_f32_e32 v54, v11
	v_sub_f32_e32 v10, v10, v159
	v_exp_f32_e32 v57, v10
	v_sub_f32_e32 v9, v9, v159
	v_exp_f32_e32 v58, v9
	v_sub_f32_e32 v8, v8, v159
	v_exp_f32_e32 v59, v8
	v_sub_f32_e32 v7, v7, v159
	v_add_f32_e32 v11, v54, v12
	v_exp_f32_e32 v7, v7
	v_add_f32_e32 v10, v57, v11
	v_add_f32_e32 v9, v58, v10
	v_add_f32_e32 v8, v59, v9
	v_add_f32_e32 v60, v7, v8
	v_cvt_pk_bf16_f32 v11, v16, v15
	v_cvt_pk_bf16_f32 v15, v59, v7
	v_cvt_pk_bf16_f32 v8, v53, v55
	v_cvt_pk_bf16_f32 v9, v52, v51
	v_cvt_pk_bf16_f32 v10, v50, v17
	v_cvt_pk_bf16_f32 v12, v14, v13
	v_cvt_pk_bf16_f32 v13, v56, v54
	v_cvt_pk_bf16_f32 v14, v57, v58
	s_xor_b64 s[82:83], s[84:85], -1
	v_add_f32_e32 v3, v3, v60
	s_mov_b32 s50, 32
	s_mov_b64 s[84:85], 0
	s_and_b64 vcc, exec, s[82:83]
	s_waitcnt lgkmcnt(0)
	v_mfma_f32_32x32x16_bf16 v[34:49], v[216:219], v[8:11], v[34:49]
	v_mfma_f32_32x32x16_bf16 v[18:33], v[224:227], v[8:11], v[18:33]
	v_mfma_f32_32x32x16_bf16 v[34:49], v[220:223], v[12:15], v[34:49]
	v_mfma_f32_32x32x16_bf16 v[18:33], v[228:231], v[12:15], v[18:33]
	s_cbranch_vccnz .LBB0_1292
.LBB0_1290:
	v_or_b32_e32 v233, s50, v6
	v_sub_u32_e32 v233, v173, v233
	v_lshl_add_u32 v233, v233, 2, s36
	v_add_u32_e32 v233, 0xffffff94, v233
	ds_read_b32 v234, v233 offset:108
	ds_read_b32 v235, v233 offset:104
	ds_read_b32 v236, v233 offset:100
	ds_read_b32 v237, v233 offset:96
	ds_read_b32 v238, v233 offset:76
	ds_read_b32 v239, v233 offset:72
	ds_read_b32 v240, v233 offset:68
	ds_read_b32 v241, v233 offset:64
	ds_read_b32 v242, v233 offset:44
	ds_read_b32 v243, v233 offset:40
	ds_read_b32 v244, v233 offset:36
	ds_read_b32 v245, v233 offset:32
	ds_read_b32 v246, v233 offset:12
	ds_read_b32 v247, v233 offset:8
	ds_read_b32 v248, v233 offset:4
	ds_read_b32 v249, v233 offset:0
	v_or_b32_e32 v7, s50, v203
	s_movk_i32 s51, 0x90
	v_mad_u32_u24 v7, v7, s51, v4
	ds_read_b128 v[8:11], v7
	ds_read_b128 v[12:15], v7 offset:32
	ds_read_b128 v[174:177], v7 offset:64
	ds_read_b128 v[178:181], v7 offset:96
	v_or_b32_e32 v7, s50, v6
	v_sub_u32_e32 v7, v173, v7
	v_add_u32_e32 v17, -1, v7
	v_add_u32_e32 v183, -2, v7
	v_add_u32_e32 v185, -3, v7
	v_add_u32_e32 v187, -8, v7
	v_add_u32_e32 v189, -9, v7
	v_add_u32_e32 v191, -10, v7
	v_add_u32_e32 v193, -11, v7
	v_add_u32_e32 v195, -16, v7
	v_subrev_u32_e32 v197, 17, v7
	v_subrev_u32_e32 v199, 18, v7
	s_waitcnt lgkmcnt(3)
	v_mfma_f32_32x32x16_bf16 v[50:65], v[8:11], v[130:133], 0
	v_subrev_u32_e32 v211, 19, v7
	v_subrev_u32_e32 v9, 24, v7
	v_subrev_u32_e32 v212, 25, v7
	v_subrev_u32_e32 v213, 26, v7
	v_subrev_u32_e32 v214, 27, v7
	s_waitcnt lgkmcnt(2)
	v_mfma_f32_32x32x16_bf16 v[50:65], v[12:15], v[134:137], v[50:65]
	s_waitcnt lgkmcnt(1)
	v_mfma_f32_32x32x16_bf16 v[50:65], v[174:177], v[138:141], v[50:65]
	s_waitcnt lgkmcnt(0)
	v_mfma_f32_32x32x16_bf16 v[50:65], v[178:181], v[142:145], v[50:65]
	v_cmp_gt_u32_e32 vcc, s65, v7
	v_or_b32_e32 v232, s50, v205
	s_movk_i32 s98, 0xc0
	v_mad_u32_u24 v232, v232, s98, v5
	ds_read_b64_tr_b16 v[216:217], v232 offset:9216
	ds_read_b64_tr_b16 v[218:219], v232 offset:10752
	ds_read_b64_tr_b16 v[220:221], v232 offset:12288
	ds_read_b64_tr_b16 v[222:223], v232 offset:13824
	ds_read_b64_tr_b16 v[224:225], v232 offset:9280
	ds_read_b64_tr_b16 v[226:227], v232 offset:10816
	ds_read_b64_tr_b16 v[228:229], v232 offset:12352
	ds_read_b64_tr_b16 v[230:231], v232 offset:13888
	s_nop 0
	v_add_f32_e32 v14, v50, v234
	v_cndmask_b32_e32 v175, v172, v14, vcc
	v_add_f32_e32 v7, v51, v235
	v_cmp_gt_u32_e32 vcc, s65, v17
	s_nop 1
	v_cndmask_b32_e32 v174, v172, v7, vcc
	v_add_f32_e32 v7, v52, v236
	v_cmp_gt_u32_e32 vcc, s65, v183
	s_nop 1
	v_cndmask_b32_e32 v52, v172, v7, vcc
	v_add_f32_e32 v7, v53, v237
	v_cmp_gt_u32_e32 vcc, s65, v185
	v_max_f32_e32 v53, v175, v174
	s_nop 0
	v_cndmask_b32_e32 v51, v172, v7, vcc
	v_add_f32_e32 v7, v54, v238
	v_cmp_gt_u32_e32 vcc, s65, v187
	v_max3_f32 v53, v53, v52, v51
	s_nop 0
	v_cndmask_b32_e32 v50, v172, v7, vcc
	v_add_f32_e32 v7, v55, v239
	v_cmp_gt_u32_e32 vcc, s65, v189
	s_nop 1
	v_cndmask_b32_e32 v17, v172, v7, vcc
	v_add_f32_e32 v7, v56, v240
	v_cmp_gt_u32_e32 vcc, s65, v191
	v_max3_f32 v53, v53, v50, v17
	s_nop 0
	v_cndmask_b32_e32 v16, v172, v7, vcc
	v_add_f32_e32 v7, v57, v241
	v_cmp_gt_u32_e32 vcc, s65, v193
	s_nop 1
	v_cndmask_b32_e32 v15, v172, v7, vcc
	v_add_f32_e32 v7, v58, v242
	v_cmp_gt_u32_e32 vcc, s65, v195
	v_max3_f32 v53, v53, v16, v15
	s_nop 0
	v_cndmask_b32_e32 v14, v172, v7, vcc
	v_add_f32_e32 v7, v59, v243
	v_cmp_gt_u32_e32 vcc, s65, v197
	s_nop 1
	v_cndmask_b32_e32 v13, v172, v7, vcc
	v_add_f32_e32 v7, v60, v244
	v_cmp_gt_u32_e32 vcc, s65, v199
	v_max3_f32 v53, v53, v14, v13
	s_nop 0
	v_cndmask_b32_e32 v12, v172, v7, vcc
	v_add_f32_e32 v7, v61, v245
	v_cmp_gt_u32_e32 vcc, s65, v211
	s_nop 1
	v_cndmask_b32_e32 v11, v172, v7, vcc
	v_add_f32_e32 v7, v62, v246
	v_cmp_gt_u32_e32 vcc, s65, v9
	v_max3_f32 v53, v53, v12, v11
	s_nop 0
	v_cndmask_b32_e32 v10, v172, v7, vcc
	v_add_f32_e32 v7, v63, v247
	v_cmp_gt_u32_e32 vcc, s65, v212
	s_nop 1
	v_cndmask_b32_e32 v9, v172, v7, vcc
	v_add_f32_e32 v7, v64, v248
	v_cmp_gt_u32_e32 vcc, s65, v213
	v_max3_f32 v53, v53, v10, v9
	s_nop 0
	v_cndmask_b32_e32 v8, v172, v7, vcc
	v_add_f32_e32 v7, v65, v249
	v_cmp_gt_u32_e32 vcc, s65, v214
	s_nop 1
	v_cndmask_b32_e32 v7, v172, v7, vcc
	v_max3_f32 v53, v53, v8, v7
	v_mov_b32_e32 v54, v53
	s_nop 1
	v_permlane32_swap_b32_e32 v53, v54
	v_max_f32_e32 v54, v54, v54
	v_max_f32_e32 v53, v53, v53
	v_max_f32_e32 v53, v53, v54
	v_add_f32_e32 v54, 0x41000000, v159
	v_cmp_gt_f32_e32 vcc, v53, v54
	s_cbranch_vccz .LBB0_1289
	v_max_f32_e32 v53, v53, v53
	v_max_f32_e32 v54, v159, v159
	v_max_f32_e32 v53, v54, v53
	v_sub_f32_e32 v54, v159, v53
	v_exp_f32_e32 v54, v54
	v_mov_b32_e32 v159, v53
	v_pk_mul_f32 v[48:49], v[48:49], v[54:55] op_sel_hi:[1,0]
	v_pk_mul_f32 v[46:47], v[46:47], v[54:55] op_sel_hi:[1,0]
	v_pk_mul_f32 v[44:45], v[44:45], v[54:55] op_sel_hi:[1,0]
	v_pk_mul_f32 v[42:43], v[42:43], v[54:55] op_sel_hi:[1,0]
	v_pk_mul_f32 v[40:41], v[40:41], v[54:55] op_sel_hi:[1,0]
	v_pk_mul_f32 v[38:39], v[38:39], v[54:55] op_sel_hi:[1,0]
	v_pk_mul_f32 v[36:37], v[36:37], v[54:55] op_sel_hi:[1,0]
	v_pk_mul_f32 v[34:35], v[34:35], v[54:55] op_sel_hi:[1,0]
	v_pk_mul_f32 v[32:33], v[32:33], v[54:55] op_sel_hi:[1,0]
	v_pk_mul_f32 v[30:31], v[30:31], v[54:55] op_sel_hi:[1,0]
	v_pk_mul_f32 v[28:29], v[28:29], v[54:55] op_sel_hi:[1,0]
	v_pk_mul_f32 v[26:27], v[26:27], v[54:55] op_sel_hi:[1,0]
	v_pk_mul_f32 v[24:25], v[24:25], v[54:55] op_sel_hi:[1,0]
	v_pk_mul_f32 v[22:23], v[22:23], v[54:55] op_sel_hi:[1,0]
	v_pk_mul_f32 v[20:21], v[20:21], v[54:55] op_sel_hi:[1,0]
	v_pk_mul_f32 v[18:19], v[18:19], v[54:55] op_sel_hi:[1,0]
	v_mul_f32_e32 v3, v3, v54
	s_branch .LBB0_1289
